# P4 output pass split 6/10 by workgroup group (alone)
# speedup vs baseline: 1.0053x; 1.0053x over previous
; __device__ __forceinline__ unsigned cvt_pk_bf16(float lo, float hi) { unsigned r; asm volatile("v_cvt_pk_bf16_f32 %0, %1, %2" : "=v"(r) : "v"(lo), "v"(hi)); return r; }
;     __device__ __forceinline__ void operator()(const f32x4 (&acc)[2][2][4][2], const Unit& u, int wr, int wc, int fr, int fq) const {
;         const int row0 = u.pm * BM + wr * 64 + fr; const int col0 = u.pn * BM + wc * 32 + 8 * fq;
; #pragma unroll
;         for (int ai = 0; ai < 2; ++ai)
; #pragma unroll
;             for (int m = 0; m < 4; ++m) { const size_t row = (size_t)(row0 + ai * HALF + m * 16); bf16_t* rowp = O + row * ldc + col0;
;                 const f32x4 p0 = *(const f32x4*)(PS + row * 16), p1 = *(const f32x4*)(PS + row * 16 + 4), p2 = *(const f32x4*)(PS + row * 16 + 8), p3 = *(const f32x4*)(PS + row * 16 + 12);
;                 const f32x4 ps = (p0 + p1) + (p2 + p3); const float rs = __builtin_amdgcn_rsqf(((ps[0] + ps[1]) + (ps[2] + ps[3])) * (1.0f / 1024.0f) + 1e-6f);
; #pragma unroll
;                 for (int bj = 0; bj < 2; ++bj) { f32x4 v0 = acc[ai][bj][m][0] * rs, v1 = acc[ai][bj][m][1] * rs;
;                     if (ACT == 2) {
; #pragma unroll
;                         for (int e = 0; e < 4; ++e) { float a = v0[e] > 0.f ? v0[e] : 0.f; v0[e] = a * a; float b = v1[e] > 0.f ? v1[e] : 0.f; v1[e] = b * b; } }
;                     u32x4 w; w.x = cvt_pk_bf16(v0[0], v0[1]); w.y = cvt_pk_bf16(v0[2], v0[3]); w.z = cvt_pk_bf16(v1[0], v1[1]); w.w = cvt_pk_bf16(v1[2], v1[3]);
;                     __builtin_nontemporal_store(w, (u32x4*)(rowp + bj * HALF)); }
.LBB0_278:
	v_lshl_or_b32 v144, s39, 8, v148
	v_lshl_add_u32 v140, s38, 8, v146
	v_ashrrev_i32_e32 v145, 31, v144
	v_mov_b64_e32 v[142:143], s[10:11]
	v_ashrrev_i32_e32 v141, 31, v140
	v_mad_i64_i32 v[150:151], s[38:39], v140, s88, v[142:143]
	v_lshlrev_b64 v[144:145], 1, v[144:145]
	v_lshl_add_u64 v[166:167], v[150:151], 0, v[144:145]
	v_lshlrev_b64 v[150:151], 6, v[140:141]
	v_lshl_add_u64 v[162:163], s[20:21], 0, v[150:151]
	global_load_dwordx4 v[150:153], v[162:163], off offset:32
	global_load_dwordx4 v[154:157], v[162:163], off offset:48
	global_load_dwordx4 v[158:161], v[162:163], off
	s_nop 0
	global_load_dwordx4 v[162:165], v[162:163], off offset:16
	s_mov_b64 s[64:65], -1
	s_and_b64 vcc, exec, s[4:5]
	s_waitcnt vmcnt(0)
	v_pk_add_f32 v[152:153], v[152:153], v[156:157]
	v_pk_add_f32 v[150:151], v[150:151], v[154:155]
	v_pk_add_f32 v[160:161], v[160:161], v[164:165]
	v_pk_add_f32 v[158:159], v[158:159], v[162:163]
	v_pk_add_f32 v[152:153], v[160:161], v[152:153]
	v_pk_add_f32 v[150:151], v[158:159], v[150:151]
	s_nop 0
	v_pk_mov_b32 v[154:155], v[150:151], v[152:153] op_sel:[1,0]
	v_mov_b32_e32 v151, v153
	v_pk_add_f32 v[150:151], v[154:155], v[150:151]
	s_nop 0
	v_add_f32_e32 v141, v150, v151
	v_fmamk_f32 v141, v141, 0x3a800000, v217
	v_rsq_f32_e32 v150, v141
	s_nop 0
	v_pk_mul_f32 v[122:123], v[122:123], v[150:151] op_sel_hi:[1,0]
	v_pk_mul_f32 v[124:125], v[124:125], v[150:151] op_sel_hi:[1,0]
	v_cvt_pk_bf16_f32 v122, v122, v123
	v_pk_mul_f32 v[128:129], v[128:129], v[150:151] op_sel_hi:[1,0]
	v_cvt_pk_bf16_f32 v123, v124, v125
	v_pk_mul_f32 v[126:127], v[126:127], v[150:151] op_sel_hi:[1,0]
	v_pk_mul_f32 v[118:119], v[118:119], v[150:151] op_sel_hi:[1,0]
	v_cvt_pk_bf16_f32 v124, v126, v127
	v_cvt_pk_bf16_f32 v125, v128, v129
	global_store_dwordx4 v[166:167], v[122:125], off nt
	v_pk_mul_f32 v[120:121], v[120:121], v[150:151] op_sel_hi:[1,0]
	s_nop 0
	v_pk_mul_f32 v[122:123], v[116:117], v[150:151] op_sel_hi:[1,0]
	v_pk_mul_f32 v[116:117], v[114:115], v[150:151] op_sel_hi:[1,0]
	v_cvt_pk_bf16_f32 v114, v118, v119
	v_cvt_pk_bf16_f32 v115, v120, v121
	s_nop 0
	v_cvt_pk_bf16_f32 v116, v116, v117
	v_cvt_pk_bf16_f32 v117, v122, v123
	global_store_dwordx4 v[166:167], v[114:117], off offset:256 nt
	s_nop 1
	v_or_b32_e32 v114, 16, v140
	v_ashrrev_i32_e32 v115, 31, v114
	v_mad_i64_i32 v[116:117], s[38:39], v114, s88, v[142:143]
	v_lshlrev_b64 v[114:115], 6, v[114:115]
	v_lshl_add_u64 v[126:127], s[20:21], 0, v[114:115]
	v_lshl_add_u64 v[150:151], v[116:117], 0, v[144:145]
	global_load_dwordx4 v[114:117], v[126:127], off offset:32
	global_load_dwordx4 v[118:121], v[126:127], off offset:48
	global_load_dwordx4 v[122:125], v[126:127], off
	s_nop 0
	global_load_dwordx4 v[126:129], v[126:127], off offset:16
	s_waitcnt vmcnt(0)
	v_pk_add_f32 v[116:117], v[116:117], v[120:121]
	v_pk_add_f32 v[114:115], v[114:115], v[118:119]
	v_pk_add_f32 v[124:125], v[124:125], v[128:129]
	v_pk_add_f32 v[122:123], v[122:123], v[126:127]
	v_pk_add_f32 v[116:117], v[124:125], v[116:117]
	v_pk_add_f32 v[114:115], v[122:123], v[114:115]
	s_nop 0
	v_pk_mov_b32 v[118:119], v[114:115], v[116:117] op_sel:[1,0]
	v_mov_b32_e32 v115, v117
	v_pk_add_f32 v[114:115], v[118:119], v[114:115]
	s_nop 0
	v_add_f32_e32 v114, v114, v115
	v_fmamk_f32 v114, v114, 0x3a800000, v217
	v_rsq_f32_e32 v114, v114
	s_nop 0
	v_pk_mul_f32 v[112:113], v[112:113], v[114:115] op_sel_hi:[1,0]
	v_pk_mul_f32 v[110:111], v[110:111], v[114:115] op_sel_hi:[1,0]
	v_pk_mul_f32 v[116:117], v[108:109], v[114:115] op_sel_hi:[1,0]
	v_pk_mul_f32 v[108:109], v[106:107], v[114:115] op_sel_hi:[1,0]
	v_cvt_pk_bf16_f32 v106, v110, v111
	v_cvt_pk_bf16_f32 v107, v112, v113
	v_pk_mul_f32 v[102:103], v[102:103], v[114:115] op_sel_hi:[1,0]
	v_cvt_pk_bf16_f32 v108, v108, v109
	v_cvt_pk_bf16_f32 v109, v116, v117
	global_store_dwordx4 v[150:151], v[106:109], off nt
	v_pk_mul_f32 v[104:105], v[104:105], v[114:115] op_sel_hi:[1,0]
	s_nop 0
	v_pk_mul_f32 v[106:107], v[100:101], v[114:115] op_sel_hi:[1,0]
	v_pk_mul_f32 v[100:101], v[98:99], v[114:115] op_sel_hi:[1,0]
	v_cvt_pk_bf16_f32 v98, v102, v103
	v_cvt_pk_bf16_f32 v99, v104, v105
	s_nop 0
	v_cvt_pk_bf16_f32 v100, v100, v101
	v_cvt_pk_bf16_f32 v101, v106, v107
	global_store_dwordx4 v[150:151], v[98:101], off offset:256 nt
	s_nop 1
	v_or_b32_e32 v98, 32, v140
	v_ashrrev_i32_e32 v99, 31, v98
	v_mad_i64_i32 v[100:101], s[38:39], v98, s88, v[142:143]
	v_lshlrev_b64 v[98:99], 6, v[98:99]
	v_lshl_add_u64 v[110:111], s[20:21], 0, v[98:99]
	v_lshl_add_u64 v[114:115], v[100:101], 0, v[144:145]
	global_load_dwordx4 v[98:101], v[110:111], off offset:32
	global_load_dwordx4 v[102:105], v[110:111], off offset:48
	global_load_dwordx4 v[106:109], v[110:111], off
	s_nop 0
	global_load_dwordx4 v[110:113], v[110:111], off offset:16
	s_waitcnt vmcnt(0)
; __device__ __forceinline__ unsigned cvt_pk_bf16(float lo, float hi) { unsigned r; asm volatile("v_cvt_pk_bf16_f32 %0, %1, %2" : "=v"(r) : "v"(lo), "v"(hi)); return r; }
;     __device__ __forceinline__ void operator()(const f32x4 (&acc)[2][2][4][2], const Unit& u, int wr, int wc, int fr, int fq) const {
;     ...
;             for (int m = 0; m < 4; ++m) { const size_t row = (size_t)(row0 + ai * HALF + m * 16); bf16_t* rowp = O + row * ldc + col0;
;                 const f32x4 p0 = *(const f32x4*)(PS + row * 16), p1 = *(const f32x4*)(PS + row * 16 + 4), p2 = *(const f32x4*)(PS + row * 16 + 8), p3 = *(const f32x4*)(PS + row * 16 + 12);
;                 const f32x4 ps = (p0 + p1) + (p2 + p3); const float rs = __builtin_amdgcn_rsqf(((ps[0] + ps[1]) + (ps[2] + ps[3])) * (1.0f / 1024.0f) + 1e-6f);
; #pragma unroll
;                 for (int bj = 0; bj < 2; ++bj) { f32x4 v0 = acc[ai][bj][m][0] * rs, v1 = acc[ai][bj][m][1] * rs;
;                     if (ACT == 2) {
; #pragma unroll
;                         for (int e = 0; e < 4; ++e) { float a = v0[e] > 0.f ? v0[e] : 0.f; v0[e] = a * a; float b = v1[e] > 0.f ? v1[e] : 0.f; v1[e] = b * b; } }
;                     u32x4 w; w.x = cvt_pk_bf16(v0[0], v0[1]); w.y = cvt_pk_bf16(v0[2], v0[3]); w.z = cvt_pk_bf16(v1[0], v1[1]); w.w = cvt_pk_bf16(v1[2], v1[3]);
;                     __builtin_nontemporal_store(w, (u32x4*)(rowp + bj * HALF)); }
	v_pk_add_f32 v[100:101], v[100:101], v[104:105]
	v_pk_add_f32 v[98:99], v[98:99], v[102:103]
	v_pk_add_f32 v[108:109], v[108:109], v[112:113]
	v_pk_add_f32 v[106:107], v[106:107], v[110:111]
	v_pk_add_f32 v[100:101], v[108:109], v[100:101]
	v_pk_add_f32 v[98:99], v[106:107], v[98:99]
	s_nop 0
	v_pk_mov_b32 v[102:103], v[98:99], v[100:101] op_sel:[1,0]
	v_mov_b32_e32 v99, v101
	v_pk_add_f32 v[98:99], v[102:103], v[98:99]
	s_nop 0
	v_add_f32_e32 v98, v98, v99
	v_fmamk_f32 v98, v98, 0x3a800000, v217
	v_rsq_f32_e32 v98, v98
	s_nop 0
	v_pk_mul_f32 v[96:97], v[96:97], v[98:99] op_sel_hi:[1,0]
	v_pk_mul_f32 v[94:95], v[94:95], v[98:99] op_sel_hi:[1,0]
	v_pk_mul_f32 v[100:101], v[92:93], v[98:99] op_sel_hi:[1,0]
	v_pk_mul_f32 v[92:93], v[90:91], v[98:99] op_sel_hi:[1,0]
	v_cvt_pk_bf16_f32 v90, v94, v95
	v_cvt_pk_bf16_f32 v91, v96, v97
	v_pk_mul_f32 v[86:87], v[86:87], v[98:99] op_sel_hi:[1,0]
	v_cvt_pk_bf16_f32 v92, v92, v93
	v_cvt_pk_bf16_f32 v93, v100, v101
	global_store_dwordx4 v[114:115], v[90:93], off nt
	v_pk_mul_f32 v[88:89], v[88:89], v[98:99] op_sel_hi:[1,0]
	s_nop 0
	v_pk_mul_f32 v[90:91], v[84:85], v[98:99] op_sel_hi:[1,0]
	v_pk_mul_f32 v[84:85], v[82:83], v[98:99] op_sel_hi:[1,0]
	v_cvt_pk_bf16_f32 v82, v86, v87
	v_cvt_pk_bf16_f32 v83, v88, v89
	s_nop 0
	v_cvt_pk_bf16_f32 v84, v84, v85
	v_cvt_pk_bf16_f32 v85, v90, v91
	global_store_dwordx4 v[114:115], v[82:85], off offset:256 nt
	s_nop 1
	v_or_b32_e32 v82, 48, v140
	v_ashrrev_i32_e32 v83, 31, v82
	v_mad_i64_i32 v[84:85], s[38:39], v82, s88, v[142:143]
	v_lshlrev_b64 v[82:83], 6, v[82:83]
	v_lshl_add_u64 v[94:95], s[20:21], 0, v[82:83]
	v_lshl_add_u64 v[98:99], v[84:85], 0, v[144:145]
	global_load_dwordx4 v[82:85], v[94:95], off offset:32
	global_load_dwordx4 v[86:89], v[94:95], off offset:48
	global_load_dwordx4 v[90:93], v[94:95], off
	s_nop 0
	global_load_dwordx4 v[94:97], v[94:95], off offset:16
	s_waitcnt vmcnt(0)
	v_pk_add_f32 v[84:85], v[84:85], v[88:89]
	v_pk_add_f32 v[82:83], v[82:83], v[86:87]
	v_pk_add_f32 v[92:93], v[92:93], v[96:97]
	v_pk_add_f32 v[90:91], v[90:91], v[94:95]
	v_pk_add_f32 v[84:85], v[92:93], v[84:85]
	v_pk_add_f32 v[82:83], v[90:91], v[82:83]
	s_nop 0
	v_pk_mov_b32 v[86:87], v[82:83], v[84:85] op_sel:[1,0]
	v_mov_b32_e32 v83, v85
	v_pk_add_f32 v[82:83], v[86:87], v[82:83]
	s_nop 0
	v_add_f32_e32 v82, v82, v83
	v_fmamk_f32 v82, v82, 0x3a800000, v217
	v_rsq_f32_e32 v82, v82
	s_nop 0
	v_pk_mul_f32 v[80:81], v[80:81], v[82:83] op_sel_hi:[1,0]
	v_pk_mul_f32 v[78:79], v[78:79], v[82:83] op_sel_hi:[1,0]
	v_pk_mul_f32 v[84:85], v[76:77], v[82:83] op_sel_hi:[1,0]
	v_pk_mul_f32 v[76:77], v[74:75], v[82:83] op_sel_hi:[1,0]
	v_cvt_pk_bf16_f32 v74, v78, v79
	v_cvt_pk_bf16_f32 v75, v80, v81
	v_pk_mul_f32 v[70:71], v[70:71], v[82:83] op_sel_hi:[1,0]
	v_cvt_pk_bf16_f32 v76, v76, v77
	v_cvt_pk_bf16_f32 v77, v84, v85
	global_store_dwordx4 v[98:99], v[74:77], off nt
	v_pk_mul_f32 v[72:73], v[72:73], v[82:83] op_sel_hi:[1,0]
	s_nop 0
	v_pk_mul_f32 v[74:75], v[68:69], v[82:83] op_sel_hi:[1,0]
	v_pk_mul_f32 v[68:69], v[66:67], v[82:83] op_sel_hi:[1,0]
	v_cvt_pk_bf16_f32 v66, v70, v71
	v_cvt_pk_bf16_f32 v67, v72, v73
	s_nop 0
	v_cvt_pk_bf16_f32 v68, v68, v69
	v_cvt_pk_bf16_f32 v69, v74, v75
	global_store_dwordx4 v[98:99], v[66:69], off offset:256 nt
	s_nop 1
	v_add_u32_e32 v66, 0x80, v140
	v_ashrrev_i32_e32 v67, 31, v66
	v_mad_i64_i32 v[68:69], s[38:39], v66, s88, v[142:143]
	v_lshlrev_b64 v[66:67], 6, v[66:67]
	v_lshl_add_u64 v[78:79], s[20:21], 0, v[66:67]
	v_lshl_add_u64 v[82:83], v[68:69], 0, v[144:145]
	global_load_dwordx4 v[66:69], v[78:79], off offset:32
	global_load_dwordx4 v[70:73], v[78:79], off offset:48
	global_load_dwordx4 v[74:77], v[78:79], off
	s_nop 0
	global_load_dwordx4 v[78:81], v[78:79], off offset:16
	s_waitcnt vmcnt(0)
	v_pk_add_f32 v[68:69], v[68:69], v[72:73]
	v_pk_add_f32 v[66:67], v[66:67], v[70:71]
	v_pk_add_f32 v[76:77], v[76:77], v[80:81]
	v_pk_add_f32 v[74:75], v[74:75], v[78:79]
	v_pk_add_f32 v[68:69], v[76:77], v[68:69]
	v_pk_add_f32 v[66:67], v[74:75], v[66:67]
	s_nop 0
	v_pk_mov_b32 v[70:71], v[66:67], v[68:69] op_sel:[1,0]
	v_mov_b32_e32 v67, v69
	v_pk_add_f32 v[66:67], v[70:71], v[66:67]
	s_nop 0
	v_add_f32_e32 v66, v66, v67
	v_fmamk_f32 v66, v66, 0x3a800000, v217
	v_rsq_f32_e32 v66, v66
	s_nop 0
	v_pk_mul_f32 v[64:65], v[64:65], v[66:67] op_sel_hi:[1,0]
	v_pk_mul_f32 v[62:63], v[62:63], v[66:67] op_sel_hi:[1,0]
	v_pk_mul_f32 v[68:69], v[60:61], v[66:67] op_sel_hi:[1,0]
	v_pk_mul_f32 v[60:61], v[58:59], v[66:67] op_sel_hi:[1,0]
	v_cvt_pk_bf16_f32 v58, v62, v63
	v_cvt_pk_bf16_f32 v59, v64, v65
	v_pk_mul_f32 v[54:55], v[54:55], v[66:67] op_sel_hi:[1,0]
	v_cvt_pk_bf16_f32 v60, v60, v61
	v_cvt_pk_bf16_f32 v61, v68, v69
	global_store_dwordx4 v[82:83], v[58:61], off nt
	v_pk_mul_f32 v[56:57], v[56:57], v[66:67] op_sel_hi:[1,0]
	s_nop 0
	v_pk_mul_f32 v[58:59], v[52:53], v[66:67] op_sel_hi:[1,0]
	v_pk_mul_f32 v[52:53], v[50:51], v[66:67] op_sel_hi:[1,0]
	v_cvt_pk_bf16_f32 v50, v54, v55
	v_cvt_pk_bf16_f32 v51, v56, v57
	s_nop 0
	v_cvt_pk_bf16_f32 v52, v52, v53
	v_cvt_pk_bf16_f32 v53, v58, v59
	global_store_dwordx4 v[82:83], v[50:53], off offset:256 nt
	s_nop 1
	v_add_u32_e32 v50, 0x90, v140
	v_ashrrev_i32_e32 v51, 31, v50
	v_mad_i64_i32 v[52:53], s[38:39], v50, s88, v[142:143]
	v_lshlrev_b64 v[50:51], 6, v[50:51]
	v_lshl_add_u64 v[62:63], s[20:21], 0, v[50:51]
	v_lshl_add_u64 v[66:67], v[52:53], 0, v[144:145]
	global_load_dwordx4 v[50:53], v[62:63], off offset:32
	global_load_dwordx4 v[54:57], v[62:63], off offset:48
	global_load_dwordx4 v[58:61], v[62:63], off
	s_nop 0
	global_load_dwordx4 v[62:65], v[62:63], off offset:16
	s_waitcnt vmcnt(0)
; __device__ __forceinline__ unsigned cvt_pk_bf16(float lo, float hi) { unsigned r; asm volatile("v_cvt_pk_bf16_f32 %0, %1, %2" : "=v"(r) : "v"(lo), "v"(hi)); return r; }
;     __device__ __forceinline__ void operator()(const f32x4 (&acc)[2][2][4][2], const Unit& u, int wr, int wc, int fr, int fq) const {
;     ...
;             for (int m = 0; m < 4; ++m) { const size_t row = (size_t)(row0 + ai * HALF + m * 16); bf16_t* rowp = O + row * ldc + col0;
;                 const f32x4 p0 = *(const f32x4*)(PS + row * 16), p1 = *(const f32x4*)(PS + row * 16 + 4), p2 = *(const f32x4*)(PS + row * 16 + 8), p3 = *(const f32x4*)(PS + row * 16 + 12);
;                 const f32x4 ps = (p0 + p1) + (p2 + p3); const float rs = __builtin_amdgcn_rsqf(((ps[0] + ps[1]) + (ps[2] + ps[3])) * (1.0f / 1024.0f) + 1e-6f);
; #pragma unroll
;                 for (int bj = 0; bj < 2; ++bj) { f32x4 v0 = acc[ai][bj][m][0] * rs, v1 = acc[ai][bj][m][1] * rs;
;                     if (ACT == 2) {
; #pragma unroll
;                         for (int e = 0; e < 4; ++e) { float a = v0[e] > 0.f ? v0[e] : 0.f; v0[e] = a * a; float b = v1[e] > 0.f ? v1[e] : 0.f; v1[e] = b * b; } }
;                     u32x4 w; w.x = cvt_pk_bf16(v0[0], v0[1]); w.y = cvt_pk_bf16(v0[2], v0[3]); w.z = cvt_pk_bf16(v1[0], v1[1]); w.w = cvt_pk_bf16(v1[2], v1[3]);
;                     __builtin_nontemporal_store(w, (u32x4*)(rowp + bj * HALF)); }
	v_pk_add_f32 v[52:53], v[52:53], v[56:57]
	v_pk_add_f32 v[50:51], v[50:51], v[54:55]
	v_pk_add_f32 v[60:61], v[60:61], v[64:65]
	v_pk_add_f32 v[58:59], v[58:59], v[62:63]
	v_pk_add_f32 v[52:53], v[60:61], v[52:53]
	v_pk_add_f32 v[50:51], v[58:59], v[50:51]
	s_nop 0
	v_pk_mov_b32 v[54:55], v[50:51], v[52:53] op_sel:[1,0]
	v_mov_b32_e32 v51, v53
	v_pk_add_f32 v[50:51], v[54:55], v[50:51]
	s_nop 0
	v_add_f32_e32 v50, v50, v51
	v_fmamk_f32 v50, v50, 0x3a800000, v217
	v_rsq_f32_e32 v50, v50
	s_nop 0
	v_pk_mul_f32 v[48:49], v[48:49], v[50:51] op_sel_hi:[1,0]
	v_pk_mul_f32 v[46:47], v[46:47], v[50:51] op_sel_hi:[1,0]
	v_pk_mul_f32 v[52:53], v[44:45], v[50:51] op_sel_hi:[1,0]
	v_pk_mul_f32 v[44:45], v[42:43], v[50:51] op_sel_hi:[1,0]
	v_cvt_pk_bf16_f32 v42, v46, v47
	v_cvt_pk_bf16_f32 v43, v48, v49
	v_pk_mul_f32 v[38:39], v[38:39], v[50:51] op_sel_hi:[1,0]
	v_cvt_pk_bf16_f32 v44, v44, v45
	v_cvt_pk_bf16_f32 v45, v52, v53
	global_store_dwordx4 v[66:67], v[42:45], off nt
	v_pk_mul_f32 v[40:41], v[40:41], v[50:51] op_sel_hi:[1,0]
	s_nop 0
	v_pk_mul_f32 v[42:43], v[36:37], v[50:51] op_sel_hi:[1,0]
	v_pk_mul_f32 v[36:37], v[34:35], v[50:51] op_sel_hi:[1,0]
	v_cvt_pk_bf16_f32 v34, v38, v39
	v_cvt_pk_bf16_f32 v35, v40, v41
	s_nop 0
	v_cvt_pk_bf16_f32 v36, v36, v37
	v_cvt_pk_bf16_f32 v37, v42, v43
	global_store_dwordx4 v[66:67], v[34:37], off offset:256 nt
	s_nop 1
	v_add_u32_e32 v34, 0xa0, v140
	v_ashrrev_i32_e32 v35, 31, v34
	v_mad_i64_i32 v[36:37], s[38:39], v34, s88, v[142:143]
	v_lshlrev_b64 v[34:35], 6, v[34:35]
	v_lshl_add_u64 v[46:47], s[20:21], 0, v[34:35]
	v_lshl_add_u64 v[50:51], v[36:37], 0, v[144:145]
	global_load_dwordx4 v[34:37], v[46:47], off offset:32
	global_load_dwordx4 v[38:41], v[46:47], off offset:48
	global_load_dwordx4 v[42:45], v[46:47], off
	s_nop 0
	global_load_dwordx4 v[46:49], v[46:47], off offset:16
	s_waitcnt vmcnt(0)
	v_pk_add_f32 v[36:37], v[36:37], v[40:41]
	v_pk_add_f32 v[34:35], v[34:35], v[38:39]
	v_pk_add_f32 v[44:45], v[44:45], v[48:49]
	v_pk_add_f32 v[42:43], v[42:43], v[46:47]
	v_pk_add_f32 v[36:37], v[44:45], v[36:37]
	v_pk_add_f32 v[34:35], v[42:43], v[34:35]
	s_nop 0
	v_pk_mov_b32 v[38:39], v[34:35], v[36:37] op_sel:[1,0]
	v_mov_b32_e32 v35, v37
	v_pk_add_f32 v[34:35], v[38:39], v[34:35]
	s_nop 0
	v_add_f32_e32 v34, v34, v35
	v_fmamk_f32 v34, v34, 0x3a800000, v217
	v_rsq_f32_e32 v34, v34
	s_nop 0
	v_pk_mul_f32 v[32:33], v[32:33], v[34:35] op_sel_hi:[1,0]
	v_pk_mul_f32 v[30:31], v[30:31], v[34:35] op_sel_hi:[1,0]
	v_pk_mul_f32 v[36:37], v[28:29], v[34:35] op_sel_hi:[1,0]
	v_pk_mul_f32 v[28:29], v[26:27], v[34:35] op_sel_hi:[1,0]
	v_cvt_pk_bf16_f32 v26, v30, v31
	v_cvt_pk_bf16_f32 v27, v32, v33
	v_pk_mul_f32 v[24:25], v[24:25], v[34:35] op_sel_hi:[1,0]
	v_cvt_pk_bf16_f32 v28, v28, v29
	v_cvt_pk_bf16_f32 v29, v36, v37
	global_store_dwordx4 v[50:51], v[26:29], off nt
	v_pk_mul_f32 v[22:23], v[22:23], v[34:35] op_sel_hi:[1,0]
	s_nop 0
	v_pk_mul_f32 v[26:27], v[20:21], v[34:35] op_sel_hi:[1,0]
	v_pk_mul_f32 v[20:21], v[18:19], v[34:35] op_sel_hi:[1,0]
	v_cvt_pk_bf16_f32 v18, v22, v23
	v_cvt_pk_bf16_f32 v19, v24, v25
	s_nop 0
	v_cvt_pk_bf16_f32 v20, v20, v21
	v_cvt_pk_bf16_f32 v21, v26, v27
	global_store_dwordx4 v[50:51], v[18:21], off offset:256 nt
	s_nop 1
	v_add_u32_e32 v20, 0xb0, v140
	v_ashrrev_i32_e32 v21, 31, v20
	v_mad_i64_i32 v[18:19], s[38:39], v20, s88, v[142:143]
	v_lshlrev_b64 v[20:21], 6, v[20:21]
	v_lshl_add_u64 v[32:33], s[20:21], 0, v[20:21]
	global_load_dwordx4 v[20:23], v[32:33], off offset:32
	global_load_dwordx4 v[24:27], v[32:33], off offset:48
	global_load_dwordx4 v[28:31], v[32:33], off
	s_nop 0
	global_load_dwordx4 v[32:35], v[32:33], off offset:16
	v_lshl_add_u64 v[18:19], v[18:19], 0, v[144:145]
	s_waitcnt vmcnt(0)
	v_pk_add_f32 v[22:23], v[22:23], v[26:27]
	v_pk_add_f32 v[20:21], v[20:21], v[24:25]
	v_pk_add_f32 v[30:31], v[30:31], v[34:35]
	v_pk_add_f32 v[28:29], v[28:29], v[32:33]
	v_pk_add_f32 v[22:23], v[30:31], v[22:23]
	v_pk_add_f32 v[20:21], v[28:29], v[20:21]
	s_nop 0
	v_pk_mov_b32 v[24:25], v[20:21], v[22:23] op_sel:[1,0]
	v_mov_b32_e32 v21, v23
	v_pk_add_f32 v[20:21], v[24:25], v[20:21]
	s_nop 0
	v_add_f32_e32 v20, v20, v21
	v_fmamk_f32 v20, v20, 0x3a800000, v217
	v_rsq_f32_e32 v20, v20
	s_nop 0
	v_pk_mul_f32 v[16:17], v[16:17], v[20:21] op_sel_hi:[1,0]
	v_pk_mul_f32 v[14:15], v[14:15], v[20:21] op_sel_hi:[1,0]
	v_pk_mul_f32 v[22:23], v[12:13], v[20:21] op_sel_hi:[1,0]
	v_pk_mul_f32 v[12:13], v[10:11], v[20:21] op_sel_hi:[1,0]
	v_cvt_pk_bf16_f32 v10, v14, v15
	v_cvt_pk_bf16_f32 v11, v16, v17
	v_pk_mul_f32 v[8:9], v[8:9], v[20:21] op_sel_hi:[1,0]
	v_cvt_pk_bf16_f32 v12, v12, v13
	v_cvt_pk_bf16_f32 v13, v22, v23
	global_store_dwordx4 v[18:19], v[10:13], off nt
	v_pk_mul_f32 v[6:7], v[6:7], v[20:21] op_sel_hi:[1,0]
	s_nop 0
	v_pk_mul_f32 v[10:11], v[4:5], v[20:21] op_sel_hi:[1,0]
	v_pk_mul_f32 v[4:5], v[2:3], v[20:21] op_sel_hi:[1,0]
	v_cvt_pk_bf16_f32 v2, v6, v7
	v_cvt_pk_bf16_f32 v3, v8, v9
	s_nop 0
	v_cvt_pk_bf16_f32 v4, v4, v5
	v_cvt_pk_bf16_f32 v5, v10, v11
	global_store_dwordx4 v[18:19], v[2:5], off offset:256 nt
	s_cbranch_vccnz .LBB0_266
	s_andn2_b64 vcc, exec, s[18:19]
	s_cbranch_vccnz .LBB0_265
	s_barrier
	s_branch .LBB0_265

; __device__ __forceinline__ void phase_lru_diff_out(int l, KIn in, const bf16* __restrict__ proj, const bf16* __restrict__ LH, const bf16* __restrict__ CP, const float* __restrict__ HIN, ...
;     float s1 = 0.f, s2 = 0.f;
;     for (int i = 0; i < 32; ++i) { s1 += in[10][l * 32 + i] * in[11][l * 32 + i]; s2 += in[12][l * 32 + i] * in[13][l * 32 + i]; }
;     const float lam_init = 0.8f - 0.6f * expf(-0.3f * (float)l), lam = expf(s1) - expf(s2) + lam_init, osc = 1.f - lam_init;
;     const float* dn = in[14] + l * 64;
; #pragma unroll 2
;     for (int idx = gid; idx < T * 32; idx += gsz) {
;         const int row = idx >> 5;
;         const int c8 = (idx & 31) * 8, b = row >> 12, ch = (row & (SEQ - 1)) >> 6, h = (idx >> 3) & 3, v8 = (idx & 7) * 8;
;         const u32x4 rlh = *(const u32x4*)(LH + (size_t)row * 256 + c8), rcp = *(const u32x4*)(CP + (size_t)row * 256 + c8), rgt = *(const u32x4*)(proj + (size_t)row * PP + C_RG + c8);
;         const float* hp = HIN + (size_t)(b * 64 + ch) * 256 + c8; const f32x4 h0 = *(const f32x4*)hp, h1 = *(const f32x4*)(hp + 4);
.LBB0_721:
	v_mov_b32_e32 v0, v216
	s_mov_b64 s[28:29], s[0:1]
	s_mov_b32 s24, s56
	s_mov_b32 s25, s55
	s_cmp_lt_u32 s55, 0x80
	s_cselect_b32 s100, 0, 0x50000
	s_mov_b32 s101, 0xfffff
	s_cselect_b32 s101, 0x5ffff, s101
	s_mov_b32 s2, 0x100000
	v_lshl_add_u32 v34, s25, 9, v0
	v_add_u32_e32 v34, s100, v34
	s_lshl_b32 s100, s100, 3
	v_cmp_gt_i32_e32 vcc, s2, v34
	s_and_saveexec_b64 s[12:13], vcc
	s_mov_b32 s30, 0xfffff
	s_cbranch_execz .LBB0_724
	s_load_dwordx2 s[14:15], s[28:29], 0x118
	s_mov_b32 s2, 0x10000
	v_cvt_f32_u32_e32 v2, s66
	s_load_dwordx8 s[4:11], s[28:29], 0x50
	s_nop 0
	s_load_dwordx2 s[28:29], s[28:29], 0x70
	s_mov_b32 s3, 0x3fb8aa3b
	s_waitcnt lgkmcnt(0)
	s_add_u32 s16, s14, 0x1b800000
	s_addc_u32 s17, s15, 0
	s_add_u32 s18, s14, 0x1c800000
	s_addc_u32 s19, s15, 0
	s_add_u32 s20, s14, 0x380000
	s_addc_u32 s21, s15, 0
	v_mul_f32_e32 v2, 0xbe99999a, v2
	s_add_u32 s22, s14, 0x1d800000
	v_mul_f32_e32 v3, 0x3fb8aa3b, v2
	s_addc_u32 s23, s15, 0
	v_fma_f32 v4, v2, s3, -v3
	v_rndne_f32_e32 v5, v3
	s_add_u32 s26, s14, 0x17800000
	v_fmac_f32_e32 v4, 0x32a5705f, v2
	v_sub_f32_e32 v3, v3, v5
	s_addc_u32 s27, s15, 0
	v_add_f32_e32 v3, v3, v4
	s_lshl_b64 s[38:39], s[70:71], 2
	v_exp_f32_e32 v3, v3
	v_cvt_i32_f32_e32 v4, v5
	s_add_u32 s28, s28, s38
	s_addc_u32 s29, s29, s39
	s_lshl_b32 s34, s66, 5
	s_lshl_b64 s[70:71], s[34:35], 2
	s_mov_b32 s33, 0xc2ce8ed0
	s_add_u32 s4, s4, s70
	v_ldexp_f32 v3, v3, v4
	v_cmp_ngt_f32_e32 vcc, s33, v2
	s_mov_b32 s40, 0x42b17218
	s_addc_u32 s5, s5, s71
	v_cndmask_b32_e32 v3, 0, v3, vcc
	v_cmp_nlt_f32_e32 vcc, s40, v2
	v_mov_b32_e32 v39, 0x7f800000
	s_add_u32 s6, s6, s70
	v_cndmask_b32_e32 v2, v39, v3, vcc
	v_mov_b32_e32 v3, 0x3f4ccccd
	s_addc_u32 s7, s7, s71
	v_fmamk_f32 v36, v2, 0xbf19999a, v3
	global_load_dwordx4 v[2:5], v1, s[4:5] offset:48
	global_load_dwordx4 v[6:9], v1, s[4:5] offset:32
	global_load_dwordx4 v[10:13], v1, s[4:5] offset:16
	global_load_dwordx4 v[14:17], v1, s[4:5]
	global_load_dwordx4 v[18:21], v1, s[6:7] offset:48
	global_load_dwordx4 v[22:25], v1, s[6:7] offset:32
	global_load_dwordx4 v[26:29], v1, s[6:7] offset:16
	global_load_dwordx4 v[30:33], v1, s[6:7]
	v_lshlrev_b32_e32 v0, 3, v0
	v_sub_f32_e32 v35, 1.0, v36
	s_waitcnt vmcnt(0)
	v_fma_f32 v37, v14, v30, 0
	v_fmac_f32_e32 v37, v15, v31
	v_fmac_f32_e32 v37, v16, v32
	v_fmac_f32_e32 v37, v17, v33
	v_fmac_f32_e32 v37, v10, v26
	v_fmac_f32_e32 v37, v11, v27
	v_fmac_f32_e32 v37, v12, v28
	v_fmac_f32_e32 v37, v13, v29
	v_fmac_f32_e32 v37, v6, v22
	v_fmac_f32_e32 v37, v7, v23
	v_fmac_f32_e32 v37, v8, v24
	v_fmac_f32_e32 v37, v9, v25
	v_fmac_f32_e32 v37, v2, v18
	v_fmac_f32_e32 v37, v3, v19
	v_fmac_f32_e32 v37, v4, v20
	v_fmac_f32_e32 v37, v5, v21
	global_load_dwordx4 v[2:5], v1, s[4:5] offset:112
	global_load_dwordx4 v[6:9], v1, s[4:5] offset:96
	global_load_dwordx4 v[10:13], v1, s[4:5] offset:80
	global_load_dwordx4 v[14:17], v1, s[4:5] offset:64
	global_load_dwordx4 v[18:21], v1, s[6:7] offset:112
	global_load_dwordx4 v[22:25], v1, s[6:7] offset:96
	global_load_dwordx4 v[26:29], v1, s[6:7] offset:80
	global_load_dwordx4 v[30:33], v1, s[6:7] offset:64
	s_add_u32 s6, s8, s70
	s_addc_u32 s7, s9, s71
	s_add_u32 s4, s10, s70
	s_addc_u32 s5, s11, s71
	s_waitcnt vmcnt(0)
	v_fmac_f32_e32 v37, v14, v30
	v_fmac_f32_e32 v37, v15, v31
	v_fmac_f32_e32 v37, v16, v32
	v_fmac_f32_e32 v37, v17, v33
	v_fmac_f32_e32 v37, v10, v26
	v_fmac_f32_e32 v37, v11, v27
	v_fmac_f32_e32 v37, v12, v28
	v_fmac_f32_e32 v37, v13, v29
	v_fmac_f32_e32 v37, v6, v22
	v_fmac_f32_e32 v37, v7, v23
	v_fmac_f32_e32 v37, v8, v24
	v_fmac_f32_e32 v37, v9, v25
	v_fmac_f32_e32 v37, v2, v18
	v_fmac_f32_e32 v37, v3, v19
	v_fmac_f32_e32 v37, v4, v20
	v_fmac_f32_e32 v37, v5, v21
	v_mul_f32_e32 v2, 0x3fb8aa3b, v37
	v_fma_f32 v3, v37, s3, -v2
	v_rndne_f32_e32 v4, v2
	v_fmac_f32_e32 v3, 0x32a5705f, v37
	v_sub_f32_e32 v2, v2, v4
	v_add_f32_e32 v2, v2, v3
	v_exp_f32_e32 v2, v2
	v_cvt_i32_f32_e32 v3, v4
	v_cmp_ngt_f32_e32 vcc, s33, v37
	v_ldexp_f32 v2, v2, v3
	s_nop 0
	v_cndmask_b32_e32 v2, 0, v2, vcc
	v_cmp_nlt_f32_e32 vcc, s40, v37
	s_nop 1
	v_cndmask_b32_e32 v37, v39, v2, vcc
	global_load_dwordx4 v[2:5], v1, s[6:7] offset:48
	global_load_dwordx4 v[6:9], v1, s[6:7] offset:32
	global_load_dwordx4 v[10:13], v1, s[6:7] offset:16
	global_load_dwordx4 v[14:17], v1, s[6:7]
	global_load_dwordx4 v[18:21], v1, s[4:5] offset:48
	global_load_dwordx4 v[22:25], v1, s[4:5] offset:32
	global_load_dwordx4 v[26:29], v1, s[4:5] offset:16
	global_load_dwordx4 v[30:33], v1, s[4:5]
	s_waitcnt vmcnt(0)
	v_fma_f32 v38, v14, v30, 0
	v_fmac_f32_e32 v38, v15, v31
	v_fmac_f32_e32 v38, v16, v32
	v_fmac_f32_e32 v38, v17, v33
	v_fmac_f32_e32 v38, v10, v26
	v_fmac_f32_e32 v38, v11, v27
	v_fmac_f32_e32 v38, v12, v28
	v_fmac_f32_e32 v38, v13, v29
	v_fmac_f32_e32 v38, v6, v22
	v_fmac_f32_e32 v38, v7, v23
	v_fmac_f32_e32 v38, v8, v24
	v_fmac_f32_e32 v38, v9, v25
	v_fmac_f32_e32 v38, v2, v18
	v_fmac_f32_e32 v38, v3, v19
	v_fmac_f32_e32 v38, v4, v20
	v_fmac_f32_e32 v38, v5, v21
	global_load_dwordx4 v[2:5], v1, s[6:7] offset:112
	global_load_dwordx4 v[10:13], v1, s[6:7] offset:96
	global_load_dwordx4 v[18:21], v1, s[6:7] offset:80
	global_load_dwordx4 v[26:29], v1, s[6:7] offset:64
	global_load_dwordx4 v[6:9], v1, s[4:5] offset:112
	global_load_dwordx4 v[14:17], v1, s[4:5] offset:96
	global_load_dwordx4 v[22:25], v1, s[4:5] offset:80
	global_load_dwordx4 v[30:33], v1, s[4:5] offset:64
	s_mov_b32 s6, 0x80000
	s_mov_b64 s[4:5], 0
	s_waitcnt vmcnt(0)
	v_fmac_f32_e32 v38, v26, v30
	v_fmac_f32_e32 v38, v27, v31
	v_fmac_f32_e32 v38, v28, v32
	v_fmac_f32_e32 v38, v29, v33
	v_fmac_f32_e32 v38, v18, v22
	v_fmac_f32_e32 v38, v19, v23
	v_fmac_f32_e32 v38, v20, v24
	v_fmac_f32_e32 v38, v21, v25
	v_fmac_f32_e32 v38, v10, v14
	v_fmac_f32_e32 v38, v11, v15
	v_fmac_f32_e32 v38, v12, v16
	v_fmac_f32_e32 v38, v13, v17
	v_fmac_f32_e32 v38, v2, v6
	v_fmac_f32_e32 v38, v3, v7
	v_fmac_f32_e32 v38, v4, v8
	v_fmac_f32_e32 v38, v5, v9
	v_mul_f32_e32 v2, 0x3fb8aa3b, v38
	v_fma_f32 v3, v38, s3, -v2
	v_rndne_f32_e32 v4, v2
	v_fmac_f32_e32 v3, 0x32a5705f, v38
	v_sub_f32_e32 v2, v2, v4
	v_add_f32_e32 v2, v2, v3
	v_exp_f32_e32 v2, v2
	v_cvt_i32_f32_e32 v3, v4
	v_cmp_ngt_f32_e32 vcc, s33, v38
	v_lshl_add_u32 v29, s25, 12, v0
	v_add_u32_e32 v29, s100, v29
	v_ldexp_f32 v2, v2, v3
	v_cndmask_b32_e32 v2, 0, v2, vcc
	v_cmp_nlt_f32_e32 vcc, s40, v38
	v_and_b32_e32 v3, 64, v241
	v_add_u32_e32 v3, 64, v3
	v_cndmask_b32_e32 v2, v39, v2, vcc
	v_sub_f32_e32 v2, v37, v2
	v_add_f32_e32 v18, v36, v2
	v_xor_b32_e32 v2, 1, v241
	v_cmp_lt_i32_e32 vcc, v2, v3
	v_mov_b32_e32 v19, v18
	s_nop 0
	v_cndmask_b32_e32 v2, v241, v2, vcc
	v_lshlrev_b32_e32 v26, 2, v2
	v_xor_b32_e32 v2, 2, v241
	v_cmp_lt_i32_e32 vcc, v2, v3
	s_nop 1
	v_cndmask_b32_e32 v2, v241, v2, vcc
	v_lshlrev_b32_e32 v27, 2, v2
	v_xor_b32_e32 v2, 4, v241
	v_cmp_lt_i32_e32 vcc, v2, v3
	s_nop 1
	v_cndmask_b32_e32 v2, v241, v2, vcc
	v_lshlrev_b32_e32 v28, 2, v2
; __device__ __forceinline__ u32x4 pack8(const float* f) { u32x4 w; w.x = pk2(f[0], f[1]); w.y = pk2(f[2], f[3]); w.z = pk2(f[4], f[5]); w.w = pk2(f[6], f[7]); return w; }
; __device__ __forceinline__ float gelu_tanh(float x) { return x / (1.f + __expf(-1.5957691216057308f * (x + 0.044715f * x * x * x))); }
; __device__ __forceinline__ void phase_lru_diff_out(int l, KIn in, const bf16* __restrict__ proj, const bf16* __restrict__ LH, const bf16* __restrict__ CP, const float* __restrict__ HIN, ...
;     ...
;     for (int idx = gid; idx < T * 32; idx += gsz) {
;         const int row = idx >> 5;
;         const int c8 = (idx & 31) * 8, b = row >> 12, ch = (row & (SEQ - 1)) >> 6, h = (idx >> 3) & 3, v8 = (idx & 7) * 8;
;         const u32x4 rlh = *(const u32x4*)(LH + (size_t)row * 256 + c8), rcp = *(const u32x4*)(CP + (size_t)row * 256 + c8), rgt = *(const u32x4*)(proj + (size_t)row * PP + C_RG + c8);
;         const float* hp = HIN + (size_t)(b * 64 + ch) * 256 + c8; const f32x4 h0 = *(const f32x4*)hp, h1 = *(const f32x4*)(hp + 4);
;         const u32x4 ra = *(const u32x4*)(OP + (size_t)row * 512 + (2 * h) * 64 + v8), rb = *(const u32x4*)(OP + (size_t)row * 512 + (2 * h + 1) * 64 + v8);
;         { float lh[8], cp[8], gt[8], o[8]; unpack8(rlh, lh); unpack8(rcp, cp); unpack8(rgt, gt);
;           const float hin[8] = {h0.x, h0.y, h0.z, h0.w, h1.x, h1.y, h1.z, h1.w};
; #pragma unroll
;           for (int e = 0; e < 8; ++e) o[e] = (lh[e] + cp[e] * hin[e]) * gelu_tanh(gt[e]);
;           *(u32x4*)(MIXO + (size_t)row * DM + 768 + c8) = pack8(o); }
.LBB0_723:
	v_ashrrev_i32_e32 v24, 5, v34
	v_ashrrev_i32_e32 v25, 31, v24
	v_and_b32_e32 v6, 0xf8, v29
	v_lshlrev_b64 v[2:3], 9, v[24:25]
	v_lshl_add_u64 v[4:5], s[16:17], 0, v[2:3]
	v_lshlrev_b32_e32 v0, 1, v6
	v_lshl_add_u64 v[2:3], s[18:19], 0, v[2:3]
	v_lshl_add_u64 v[4:5], v[4:5], 0, v[0:1]
	v_lshl_add_u64 v[2:3], v[2:3], 0, v[0:1]
	global_load_dwordx4 v[10:13], v[4:5], off
	global_load_dwordx4 v[14:17], v[2:3], off
	v_mov_b64_e32 v[2:3], s[14:15]
	v_mad_i64_i32 v[2:3], s[8:9], v24, s88, v[2:3]
	v_lshl_add_u64 v[2:3], v[2:3], 0, v[0:1]
	s_mov_b32 s3, 0xd801000
	v_add_co_u32_e32 v2, vcc, s3, v2
	v_lshrrev_b32_e32 v7, 6, v24
	s_nop 0
	v_addc_co_u32_e32 v3, vcc, 0, v3, vcc
	global_load_dwordx4 v[36:39], v[2:3], off
	v_ashrrev_i32_e32 v2, 11, v34
	v_bfi_b32 v2, 63, v7, v2
	v_ashrrev_i32_e32 v3, 31, v2
	v_lshlrev_b64 v[2:3], 10, v[2:3]
	v_lshl_add_u64 v[2:3], s[20:21], 0, v[2:3]
	v_lshlrev_b32_e32 v4, 2, v6
	v_mov_b32_e32 v5, v1
	v_lshl_add_u64 v[2:3], v[2:3], 0, v[4:5]
	global_load_dwordx4 v[40:43], v[2:3], off offset:16
	global_load_dwordx4 v[44:47], v[2:3], off
	v_bfe_u32 v8, v34, 3, 2
	v_lshlrev_b64 v[2:3], 10, v[24:25]
	v_and_b32_e32 v30, 56, v29
	v_lshl_add_u64 v[2:3], s[22:23], 0, v[2:3]
	v_lshlrev_b32_e32 v4, 8, v8
	v_lshl_add_u64 v[2:3], v[2:3], 0, v[4:5]
	v_lshlrev_b32_e32 v22, 1, v30
	v_mov_b32_e32 v23, v1
	v_lshl_add_u64 v[2:3], v[2:3], 0, v[22:23]
	v_lshlrev_b32_e32 v20, 7, v8
	global_load_dwordx4 v[6:9], v[2:3], off
	s_nop 0
	global_load_dwordx4 v[2:5], v[2:3], off offset:128
	v_mov_b32_e32 v21, v1
	v_add_u32_e32 v34, s2, v34
	v_add_u32_e32 v29, s6, v29
	s_waitcnt vmcnt(6)
	v_lshlrev_b32_e32 v32, 16, v10
	v_and_b32_e32 v33, 0xffff0000, v10
	s_waitcnt vmcnt(5)
	v_lshlrev_b32_e32 v48, 16, v14
	v_and_b32_e32 v49, 0xffff0000, v14
	s_waitcnt vmcnt(4)
	v_lshlrev_b32_e32 v10, 16, v36
	v_mul_f32_e32 v31, 0x3d372713, v10
	v_mul_f32_e32 v31, v31, v10
	v_fma_f32 v31, v31, v10, v10
	v_mul_f32_e32 v31, 0xbfcc422a, v31
	v_and_b32_e32 v14, 0xffff0000, v36
	v_mul_f32_e32 v31, 0x3fb8aa3b, v31
	v_exp_f32_e32 v50, v31
	v_mul_f32_e32 v31, 0x3d372713, v14
	v_mul_f32_e32 v31, v31, v14
	v_fma_f32 v31, v31, v14, v14
	v_mul_f32_e32 v31, 0xbfcc422a, v31
	v_mul_f32_e32 v31, 0x3fb8aa3b, v31
	v_exp_f32_e32 v51, v31
	s_waitcnt vmcnt(2)
	v_pk_fma_f32 v[32:33], v[44:45], v[48:49], v[32:33]
	v_pk_add_f32 v[44:45], v[50:51], 1.0 op_sel_hi:[1,0]
	s_nop 0
	v_div_scale_f32 v31, s[8:9], v45, v45, v14
	v_rcp_f32_e32 v36, v31
	s_nop 0
	v_fma_f32 v48, -v31, v36, 1.0
	v_fmac_f32_e32 v36, v48, v36
	v_div_scale_f32 v48, vcc, v14, v45, v14
	v_mul_f32_e32 v49, v48, v36
	v_fma_f32 v50, -v31, v49, v48
	v_fmac_f32_e32 v49, v50, v36
	v_fma_f32 v31, -v31, v49, v48
	v_div_fmas_f32 v31, v31, v36, v49
	v_div_fixup_f32 v45, v31, v45, v14
	v_div_scale_f32 v14, s[8:9], v44, v44, v10
	v_rcp_f32_e32 v31, v14
	s_nop 0
	v_fma_f32 v36, -v14, v31, 1.0
	v_fmac_f32_e32 v31, v36, v31
	v_div_scale_f32 v36, vcc, v10, v44, v10
	v_mul_f32_e32 v48, v36, v31
	v_fma_f32 v49, -v14, v48, v36
	v_fmac_f32_e32 v48, v49, v31
	v_fma_f32 v14, -v14, v48, v36
	v_div_fmas_f32 v14, v14, v31, v48
	v_div_fixup_f32 v44, v14, v44, v10
	v_pk_mul_f32 v[32:33], v[32:33], v[44:45]
	v_lshlrev_b32_e32 v10, 16, v11
	v_and_b32_e32 v11, 0xffff0000, v11
	v_lshlrev_b32_e32 v14, 16, v15
	v_and_b32_e32 v15, 0xffff0000, v15
	v_lshlrev_b32_e32 v31, 16, v37
	v_and_b32_e32 v44, 0xffff0000, v37
	v_mul_f32_e32 v36, 0x3d372713, v31
	v_pk_fma_f32 v[10:11], v[46:47], v[14:15], v[10:11]
	v_mul_f32_e32 v14, 0x3d372713, v44
	v_mul_f32_e32 v36, v36, v31
	v_mul_f32_e32 v14, v14, v44
	v_fma_f32 v36, v36, v31, v31
	v_fma_f32 v14, v14, v44, v44
	v_mul_f32_e32 v36, 0xbfcc422a, v36
	v_mul_f32_e32 v14, 0xbfcc422a, v14
	v_mul_f32_e32 v36, 0x3fb8aa3b, v36
	v_mul_f32_e32 v14, 0x3fb8aa3b, v14
	v_exp_f32_e32 v36, v36
	v_exp_f32_e32 v37, v14
	s_nop 0
	v_pk_add_f32 v[14:15], v[36:37], 1.0 op_sel_hi:[1,0]
	s_nop 0
	v_div_scale_f32 v36, s[8:9], v15, v15, v44
	v_rcp_f32_e32 v37, v36
	s_nop 0
	v_fma_f32 v45, -v36, v37, 1.0
	v_fmac_f32_e32 v37, v45, v37
	v_div_scale_f32 v45, vcc, v44, v15, v44
	v_mul_f32_e32 v46, v45, v37
	v_fma_f32 v47, -v36, v46, v45
	v_fmac_f32_e32 v46, v47, v37
	v_fma_f32 v36, -v36, v46, v45
	v_div_fmas_f32 v36, v36, v37, v46
	v_div_fixup_f32 v15, v36, v15, v44
	v_div_scale_f32 v36, s[8:9], v14, v14, v31
	v_rcp_f32_e32 v37, v36
	s_nop 0
	v_fma_f32 v44, -v36, v37, 1.0
	v_fmac_f32_e32 v37, v44, v37
	v_div_scale_f32 v44, vcc, v31, v14, v31
	v_mul_f32_e32 v45, v44, v37
	v_fma_f32 v46, -v36, v45, v44
	v_fmac_f32_e32 v45, v46, v37
	v_fma_f32 v36, -v36, v45, v44
	v_div_fmas_f32 v36, v36, v37, v45
	v_div_fixup_f32 v14, v36, v14, v31
	v_pk_mul_f32 v[10:11], v[10:11], v[14:15]
	v_lshlrev_b32_e32 v14, 16, v12
	v_and_b32_e32 v15, 0xffff0000, v12
	v_lshlrev_b32_e32 v12, 16, v38
	v_mul_f32_e32 v31, 0x3d372713, v12
	v_mul_f32_e32 v31, v31, v12
	v_fma_f32 v31, v31, v12, v12
	v_mul_f32_e32 v31, 0xbfcc422a, v31
	v_lshlrev_b32_e32 v36, 16, v16
	v_and_b32_e32 v37, 0xffff0000, v16
	v_and_b32_e32 v16, 0xffff0000, v38
	v_mul_f32_e32 v31, 0x3fb8aa3b, v31
	v_exp_f32_e32 v44, v31
	v_mul_f32_e32 v31, 0x3d372713, v16
	v_mul_f32_e32 v31, v31, v16
	v_fma_f32 v31, v31, v16, v16
	v_mul_f32_e32 v31, 0xbfcc422a, v31
	v_mul_f32_e32 v31, 0x3fb8aa3b, v31
	v_exp_f32_e32 v45, v31
	v_pk_fma_f32 v[14:15], v[40:41], v[36:37], v[14:15]
; __device__ __forceinline__ u32x4 pack8(const float* f) { u32x4 w; w.x = pk2(f[0], f[1]); w.y = pk2(f[2], f[3]); w.z = pk2(f[4], f[5]); w.w = pk2(f[6], f[7]); return w; }
; __device__ __forceinline__ float gelu_tanh(float x) { return x / (1.f + __expf(-1.5957691216057308f * (x + 0.044715f * x * x * x))); }
; __device__ __forceinline__ void phase_lru_diff_out(int l, KIn in, const bf16* __restrict__ proj, const bf16* __restrict__ LH, const bf16* __restrict__ CP, const float* __restrict__ HIN, ...
;     ...
;           for (int e = 0; e < 8; ++e) o[e] = (lh[e] + cp[e] * hin[e]) * gelu_tanh(gt[e]);
;           *(u32x4*)(MIXO + (size_t)row * DM + 768 + c8) = pack8(o); }
;         { float a[8], bq[8], o[8]; unpack8(ra, a); unpack8(rb, bq); float ss = 0.f;
; #pragma unroll
;           for (int e = 0; e < 8; ++e) { o[e] = a[e] - lam * bq[e]; ss += o[e] * o[e]; }
;           ss += __shfl_xor(ss, 1); ss += __shfl_xor(ss, 2); ss += __shfl_xor(ss, 4);
;           const float rstd = rsqrtf(ss * (1.f / 64.f) + EPS) * osc;
; #pragma unroll
;           for (int e = 0; e < 8; ++e) o[e] = o[e] * rstd * dn[v8 + e];
;           *(u32x4*)(MIXO + (size_t)row * DM + 256 + h * 64 + v8) = pack8(o); }
;     }
	v_pk_add_f32 v[36:37], v[44:45], 1.0 op_sel_hi:[1,0]
	s_nop 0
	v_div_scale_f32 v31, s[8:9], v37, v37, v16
	v_rcp_f32_e32 v38, v31
	s_nop 0
	v_fma_f32 v40, -v31, v38, 1.0
	v_fmac_f32_e32 v38, v40, v38
	v_div_scale_f32 v40, vcc, v16, v37, v16
	v_mul_f32_e32 v41, v40, v38
	v_fma_f32 v44, -v31, v41, v40
	v_fmac_f32_e32 v41, v44, v38
	v_fma_f32 v31, -v31, v41, v40
	v_div_fmas_f32 v31, v31, v38, v41
	v_div_fixup_f32 v37, v31, v37, v16
	v_div_scale_f32 v16, s[8:9], v36, v36, v12
	v_rcp_f32_e32 v31, v16
	s_nop 0
	v_fma_f32 v38, -v16, v31, 1.0
	v_fmac_f32_e32 v31, v38, v31
	v_div_scale_f32 v38, vcc, v12, v36, v12
	v_mul_f32_e32 v40, v38, v31
	v_fma_f32 v41, -v16, v40, v38
	v_fmac_f32_e32 v40, v41, v31
	v_fma_f32 v16, -v16, v40, v38
	v_div_fmas_f32 v16, v16, v31, v40
	v_div_fixup_f32 v36, v16, v36, v12
	v_pk_mul_f32 v[36:37], v[14:15], v[36:37]
	v_lshlrev_b32_e32 v12, 16, v13
	v_and_b32_e32 v13, 0xffff0000, v13
	v_lshlrev_b32_e32 v14, 16, v17
	v_and_b32_e32 v15, 0xffff0000, v17
	v_lshlrev_b32_e32 v31, 16, v39
	v_and_b32_e32 v38, 0xffff0000, v39
	v_mul_f32_e32 v16, 0x3d372713, v31
	v_pk_fma_f32 v[12:13], v[42:43], v[14:15], v[12:13]
	v_mul_f32_e32 v14, 0x3d372713, v38
	v_mul_f32_e32 v16, v16, v31
	v_mul_f32_e32 v14, v14, v38
	v_fma_f32 v16, v16, v31, v31
	v_fma_f32 v14, v14, v38, v38
	v_mul_f32_e32 v16, 0xbfcc422a, v16
	v_mul_f32_e32 v14, 0xbfcc422a, v14
	v_mul_f32_e32 v16, 0x3fb8aa3b, v16
	v_mul_f32_e32 v14, 0x3fb8aa3b, v14
	v_exp_f32_e32 v16, v16
	v_exp_f32_e32 v17, v14
	s_nop 0
	v_pk_add_f32 v[14:15], v[16:17], 1.0 op_sel_hi:[1,0]
	s_nop 0
	v_div_scale_f32 v16, s[8:9], v15, v15, v38
	v_rcp_f32_e32 v17, v16
	s_nop 0
	v_fma_f32 v39, -v16, v17, 1.0
	v_fmac_f32_e32 v17, v39, v17
	v_div_scale_f32 v39, vcc, v38, v15, v38
	v_mul_f32_e32 v40, v39, v17
	v_fma_f32 v41, -v16, v40, v39
	v_fmac_f32_e32 v40, v41, v17
	v_fma_f32 v16, -v16, v40, v39
	v_div_fmas_f32 v16, v16, v17, v40
	v_div_fixup_f32 v15, v16, v15, v38
	v_div_scale_f32 v16, s[8:9], v14, v14, v31
	v_rcp_f32_e32 v17, v16
	s_waitcnt vmcnt(1)
	v_and_b32_e32 v41, 0xffff0000, v6
	v_fma_f32 v38, -v16, v17, 1.0
	v_fmac_f32_e32 v17, v38, v17
	v_div_scale_f32 v38, vcc, v31, v14, v31
	v_mul_f32_e32 v39, v38, v17
	v_fma_f32 v40, -v16, v39, v38
	v_fmac_f32_e32 v39, v40, v17
	v_fma_f32 v16, -v16, v39, v38
	v_div_fmas_f32 v16, v16, v17, v39
	v_div_fixup_f32 v14, v16, v14, v31
	v_pk_mul_f32 v[12:13], v[12:13], v[14:15]
	v_cvt_pk_bf16_f32 v15, v10, v11
	v_lshlrev_b64 v[10:11], 11, v[24:25]
	v_cvt_pk_bf16_f32 v17, v12, v13
	v_lshl_add_u64 v[12:13], s[26:27], 0, v[10:11]
	v_cvt_pk_bf16_f32 v14, v32, v33
	v_cvt_pk_bf16_f32 v16, v36, v37
	v_lshl_add_u64 v[10:11], v[12:13], 0, v[0:1]
	global_store_dwordx4 v[10:11], v[14:17], off offset:1536
	v_lshlrev_b32_e32 v10, 16, v9
	v_and_b32_e32 v11, 0xffff0000, v9
	s_waitcnt vmcnt(1)
	v_lshlrev_b32_e32 v14, 16, v5
	v_and_b32_e32 v15, 0xffff0000, v5
	v_lshlrev_b32_e32 v0, 2, v30
	v_pk_fma_f32 v[14:15], v[18:19], v[14:15], v[10:11] neg_lo:[1,0,0] neg_hi:[1,0,0]
	v_lshlrev_b32_e32 v10, 16, v8
	v_and_b32_e32 v11, 0xffff0000, v8
	v_lshlrev_b32_e32 v8, 16, v4
	v_and_b32_e32 v9, 0xffff0000, v4
	v_pk_fma_f32 v[4:5], v[18:19], v[8:9], v[10:11] neg_lo:[1,0,0] neg_hi:[1,0,0]
	global_load_dwordx4 v[8:11], v0, s[28:29] offset:16
	global_load_dwordx4 v[30:33], v0, s[28:29]
	v_lshlrev_b32_e32 v36, 16, v7
	v_and_b32_e32 v37, 0xffff0000, v7
	v_lshlrev_b32_e32 v40, 16, v6
	v_lshlrev_b32_e32 v6, 16, v2
	v_and_b32_e32 v7, 0xffff0000, v2
	v_lshlrev_b32_e32 v38, 16, v3
	v_and_b32_e32 v39, 0xffff0000, v3
	v_pk_fma_f32 v[2:3], v[18:19], v[6:7], v[40:41] neg_lo:[1,0,0] neg_hi:[1,0,0]
	v_pk_fma_f32 v[36:37], v[18:19], v[38:39], v[36:37] neg_lo:[1,0,0] neg_hi:[1,0,0]
	v_pk_mul_f32 v[6:7], v[2:3], v[2:3]
	v_pk_mul_f32 v[38:39], v[36:37], v[36:37]
	v_add_f32_e32 v0, v6, v7
	v_add_f32_e32 v0, v38, v0
	v_pk_mul_f32 v[24:25], v[4:5], v[4:5]
	v_add_f32_e32 v0, v39, v0
	v_add_f32_e32 v0, v24, v0
	v_pk_mul_f32 v[16:17], v[14:15], v[14:15]
	v_add_f32_e32 v0, v25, v0
	v_add_f32_e32 v0, v16, v0
	v_add_f32_e32 v0, v17, v0
	ds_bpermute_b32 v6, v26, v0
	s_waitcnt lgkmcnt(0)
	v_add_f32_e32 v0, v0, v6
	ds_bpermute_b32 v6, v27, v0
	s_waitcnt lgkmcnt(0)
	v_add_f32_e32 v0, v0, v6
	ds_bpermute_b32 v6, v28, v0
	s_waitcnt lgkmcnt(0)
	v_add_f32_e32 v0, v0, v6
	v_fmamk_f32 v0, v0, 0x3c800000, v217
	v_cmp_gt_f32_e32 vcc, s45, v0
	v_mul_f32_e32 v6, 0x4b800000, v0
	s_nop 0
	v_cndmask_b32_e32 v0, v0, v6, vcc
	v_rsq_f32_e32 v0, v0
	s_nop 0
	v_mul_f32_e32 v6, 0x45800000, v0
	v_cndmask_b32_e32 v0, v0, v6, vcc
	v_mul_f32_e32 v0, v35, v0
	v_pk_mul_f32 v[2:3], v[2:3], v[0:1] op_sel_hi:[1,0]
	v_pk_mul_f32 v[6:7], v[36:37], v[0:1] op_sel_hi:[1,0]
	v_pk_mul_f32 v[4:5], v[4:5], v[0:1] op_sel_hi:[1,0]
	v_cmp_lt_i32_e32 vcc, s101, v34
	s_or_b64 s[4:5], vcc, s[4:5]
	s_waitcnt vmcnt(1)
	v_pk_mul_f32 v[4:5], v[8:9], v[4:5]
	s_waitcnt vmcnt(0)
	v_pk_mul_f32 v[2:3], v[30:31], v[2:3]
	v_pk_mul_f32 v[6:7], v[32:33], v[6:7]
	v_pk_mul_f32 v[8:9], v[14:15], v[0:1] op_sel_hi:[1,0]
	v_cvt_pk_bf16_f32 v2, v2, v3
	v_pk_mul_f32 v[8:9], v[10:11], v[8:9]
	v_cvt_pk_bf16_f32 v3, v6, v7
	v_lshl_add_u64 v[6:7], v[12:13], 0, v[20:21]
	v_cvt_pk_bf16_f32 v4, v4, v5
	v_cvt_pk_bf16_f32 v5, v8, v9
	v_lshl_add_u64 v[6:7], v[6:7], 0, v[22:23]
	global_store_dwordx4 v[6:7], v[2:5], off offset:512
	s_andn2_b64 exec, exec, s[4:5]
	s_cbranch_execnz .LBB0_723

;     __device__ __forceinline__ void fused(f32x4 (&acc)[2][2][4][2], const Unit& u, int wr, int wc, int fr, int fq, PG8_LAS unsigned char* lds, int wid, int lane) const {
;     ...
;         if constexpr (PRESCALE) {
; #pragma unroll
;             for (int ai = 0; ai < 2; ++ai)
; #pragma unroll
;                 for (int m = 0; m < 4; ++m) { const f32x4 p = *(const f32x4*)(PSin + (size_t)(u.pm * BM + ai * HALF + wr * 64 + m * 16 + fr) * 16 + 4 * fq);
;                     float s = (p[0] + p[1]) + (p[2] + p[3]); s += __shfl_xor(s, 16); s += __shfl_xor(s, 32);
;                     const float r2 = __builtin_amdgcn_rcpf(s * (1.0f / 1024.0f) + 1e-6f);
; #pragma unroll
;                     for (int bj = 0; bj < 2; ++bj)
; #pragma unroll
;                         for (int n = 0; n < 2; ++n) acc[ai][bj][m][n] = acc[ai][bj][m][n] * r2; } }
;     ...
;             for (int m = 0; m < 4; ++m) { const size_t off = (size_t)(u.pm * BM + ai * HALF + wr * 64 + m * 16 + fr) * ldc + col0;
; #pragma unroll
.LBB0_1110:
	s_lshl_b64 s[4:5], s[34:35], 6
	s_add_u32 s3, s14, s4
	s_addc_u32 s4, s15, s5
	v_lshrrev_b32_e32 v0, 2, v187
	v_and_b32_e32 v3, 64, v241
	s_add_u32 s68, s3, 0x7000000
	v_and_b32_e32 v2, 12, v0
	v_xor_b32_e32 v0, 16, v241
	v_add_u32_e32 v3, 64, v3
	s_addc_u32 s69, s4, 0
	s_lshl_b32 s82, s30, 8
	v_cmp_lt_i32_e32 vcc, v0, v3
	s_add_i32 s4, s82, s41
	v_or_b32_e32 v132, s4, v188
	v_cndmask_b32_e32 v0, v241, v0, vcc
	v_lshlrev_b32_e32 v184, 2, v0
	v_xor_b32_e32 v0, 32, v241
	v_cmp_lt_i32_e32 vcc, v0, v3
	v_ashrrev_i32_e32 v133, 31, v132
	v_lshlrev_b64 v[134:135], 6, v[132:133]
	v_cndmask_b32_e32 v0, v241, v0, vcc
	v_lshlrev_b32_e32 v185, 2, v0
	v_lshl_add_u64 v[134:135], s[68:69], 0, v[134:135]
	v_lshlrev_b32_e32 v0, 2, v2
	v_lshl_add_u64 v[134:135], v[134:135], 0, v[0:1]
	s_barrier
	global_load_dwordx4 v[134:137], v[134:135], off
	s_lshl_b32 s3, s90, 5
	s_lshl_b32 s4, s70, 8
	s_or_b32 s3, s4, s3
	v_or_b32_e32 v2, s3, v2
	v_and_b32_e32 v189, 63, v187
	s_lshl_b32 s3, s90, 3
	v_cmp_gt_u32_e64 s[4:5], 16, v189
	s_add_i32 s3, s3, 0
	s_waitcnt vmcnt(0)
	v_mov_b32_e32 v138, v135
	v_mov_b32_e32 v139, v136
	v_mov_b32_e32 v135, v137
	v_pk_add_f32 v[134:135], v[138:139], v[134:135]
	s_nop 0
	v_add_f32_e32 v3, v134, v135
	ds_bpermute_b32 v134, v184, v3
	s_waitcnt lgkmcnt(0)
	v_add_f32_e32 v3, v3, v134
	ds_bpermute_b32 v134, v185, v3
	s_waitcnt lgkmcnt(0)
	v_add_f32_e32 v3, v3, v134
	v_or_b32_e32 v134, 16, v132
	v_ashrrev_i32_e32 v135, 31, v134
	v_lshlrev_b64 v[136:137], 6, v[134:135]
	v_lshl_add_u64 v[136:137], s[68:69], 0, v[136:137]
	v_lshl_add_u64 v[136:137], v[136:137], 0, v[0:1]
	global_load_dwordx4 v[136:139], v[136:137], off
	v_fmamk_f32 v3, v3, 0x3a800000, v217
	v_rcp_f32_e32 v180, v3
	s_waitcnt vmcnt(0)
	v_mov_b32_e32 v140, v137
	v_mov_b32_e32 v141, v138
	v_mov_b32_e32 v137, v139
	v_pk_add_f32 v[136:137], v[140:141], v[136:137]
	v_pk_mul_f32 v[160:161], v[130:131], v[180:181] op_sel_hi:[1,0]
	v_add_f32_e32 v3, v136, v137
	ds_bpermute_b32 v136, v184, v3
	v_pk_mul_f32 v[162:163], v[128:129], v[180:181] op_sel_hi:[1,0]
	v_pk_mul_f32 v[156:157], v[126:127], v[180:181] op_sel_hi:[1,0]
	v_pk_mul_f32 v[158:159], v[124:125], v[180:181] op_sel_hi:[1,0]
	v_pk_mul_f32 v[150:151], v[122:123], v[180:181] op_sel_hi:[1,0]
	v_pk_mul_f32 v[152:153], v[120:121], v[180:181] op_sel_hi:[1,0]
	v_pk_mul_f32 v[146:147], v[118:119], v[180:181] op_sel_hi:[1,0]
	v_pk_mul_f32 v[148:149], v[116:117], v[180:181] op_sel_hi:[1,0]
	s_waitcnt lgkmcnt(0)
	v_add_f32_e32 v181, v3, v136
	v_or_b32_e32 v136, 32, v132
	v_ashrrev_i32_e32 v137, 31, v136
	v_lshlrev_b64 v[138:139], 6, v[136:137]
	v_lshl_add_u64 v[138:139], s[68:69], 0, v[138:139]
	v_lshl_add_u64 v[138:139], v[138:139], 0, v[0:1]
	global_load_dwordx4 v[138:141], v[138:139], off
	v_mov_b32_e32 v202, v162
	v_mov_b32_e32 v203, v161
	v_mov_b32_e32 v210, v158
	v_mov_b32_e32 v211, v157
	v_add_f32_e32 v213, v150, v151
	v_mov_b32_e32 v212, v149
	ds_bpermute_b32 v201, v185, v181
	s_waitcnt vmcnt(0)
	v_mov_b32_e32 v142, v139
	v_mov_b32_e32 v143, v140
	v_mov_b32_e32 v139, v141
	v_pk_add_f32 v[138:139], v[142:143], v[138:139]
	s_nop 0
	v_add_f32_e32 v3, v138, v139
	ds_bpermute_b32 v138, v184, v3
	s_waitcnt lgkmcnt(0)
	v_add_f32_e32 v199, v3, v138
	v_or_b32_e32 v138, 48, v132
	v_ashrrev_i32_e32 v139, 31, v138
	v_lshlrev_b64 v[140:141], 6, v[138:139]
	v_lshl_add_u64 v[140:141], s[68:69], 0, v[140:141]
	v_lshl_add_u64 v[140:141], v[140:141], 0, v[0:1]
	global_load_dwordx4 v[140:143], v[140:141], off
	ds_bpermute_b32 v200, v185, v199
	s_waitcnt vmcnt(0)
	v_mov_b32_e32 v144, v141
	v_mov_b32_e32 v145, v142
	v_mov_b32_e32 v141, v143
	v_pk_add_f32 v[140:141], v[144:145], v[140:141]
	s_nop 0
	v_add_f32_e32 v3, v140, v141
	ds_bpermute_b32 v140, v184, v3
	s_waitcnt lgkmcnt(0)
	v_add_f32_e32 v197, v3, v140
	v_add_u32_e32 v140, 0x80, v132
	v_ashrrev_i32_e32 v141, 31, v140
	v_lshlrev_b64 v[140:141], 6, v[140:141]
	v_lshl_add_u64 v[140:141], s[68:69], 0, v[140:141]
	v_lshl_add_u64 v[140:141], v[140:141], 0, v[0:1]
	global_load_dwordx4 v[140:143], v[140:141], off
	ds_bpermute_b32 v198, v185, v197
	s_waitcnt vmcnt(0)
	v_mov_b32_e32 v144, v141
	v_mov_b32_e32 v145, v142
	v_mov_b32_e32 v141, v143
	v_pk_add_f32 v[140:141], v[144:145], v[140:141]
	s_nop 0
	v_add_f32_e32 v3, v140, v141
	ds_bpermute_b32 v140, v184, v3
	s_waitcnt lgkmcnt(0)
	v_add_f32_e32 v195, v3, v140
	v_add_u32_e32 v140, 0x90, v132
	v_ashrrev_i32_e32 v141, 31, v140
	v_lshlrev_b64 v[140:141], 6, v[140:141]
	v_lshl_add_u64 v[140:141], s[68:69], 0, v[140:141]
	v_lshl_add_u64 v[140:141], v[140:141], 0, v[0:1]
	global_load_dwordx4 v[140:143], v[140:141], off
	ds_bpermute_b32 v196, v185, v195
	s_waitcnt vmcnt(0)
	v_mov_b32_e32 v144, v141
	v_mov_b32_e32 v145, v142
	v_mov_b32_e32 v141, v143
	v_pk_add_f32 v[140:141], v[144:145], v[140:141]
	s_nop 0
	v_add_f32_e32 v3, v140, v141
	ds_bpermute_b32 v140, v184, v3
	s_waitcnt lgkmcnt(0)
	v_add_f32_e32 v193, v3, v140
	v_add_u32_e32 v140, 0xa0, v132
	v_ashrrev_i32_e32 v141, 31, v140
	v_lshlrev_b64 v[140:141], 6, v[140:141]
	v_lshl_add_u64 v[140:141], s[68:69], 0, v[140:141]
	v_lshl_add_u64 v[140:141], v[140:141], 0, v[0:1]
	global_load_dwordx4 v[140:143], v[140:141], off
	ds_bpermute_b32 v194, v185, v193
	s_waitcnt vmcnt(0)
;     __device__ __forceinline__ bool run(const f32x4 (&v)[2][2][4][2], const Unit& u, int wr, int wc, int fr, int fq, PG8_LAS unsigned char* lds, int wid, int lane) const {
;     ...
;                 float s = 0.f;
; #pragma unroll
;                 for (int bj = 0; bj < 2; ++bj)
; #pragma unroll
;                     for (int n = 0; n < 2; ++n) { const f32x4 x = v[ai][bj][m][n]; s += (x[0] + x[1]) + (x[2] + x[3]); }
;                 s += __shfl_xor(s, 16); s += __shfl_xor(s, 32);
;                 const float mw = s * (1.0f / 64.0f); float q = 0.f;
; #pragma unroll
;                 for (int bj = 0; bj < 2; ++bj)
; #pragma unroll
;                     for (int n = 0; n < 2; ++n) { const f32x4 d = v[ai][bj][m][n] - mw; q += (d[0] * d[0] + d[1] * d[1]) + (d[2] * d[2] + d[3] * d[3]); }
;                 q += __shfl_xor(q, 16); q += __shfl_xor(q, 32);
;                 if (fq == 0) P[(ai * HALF + wr * 64 + m * 16 + fr) * 4 + wc] = (f32x2v){mw, q};
;     __device__ __forceinline__ void fused(f32x4 (&acc)[2][2][4][2], const Unit& u, int wr, int wc, int fr, int fq, PG8_LAS unsigned char* lds, int wid, int lane) const {
;     ...
;                 for (int m = 0; m < 4; ++m) { const f32x4 p = *(const f32x4*)(PSin + (size_t)(u.pm * BM + ai * HALF + wr * 64 + m * 16 + fr) * 16 + 4 * fq);
;                     float s = (p[0] + p[1]) + (p[2] + p[3]); s += __shfl_xor(s, 16); s += __shfl_xor(s, 32);
;                     const float r2 = __builtin_amdgcn_rcpf(s * (1.0f / 1024.0f) + 1e-6f);
; #pragma unroll
;                     for (int bj = 0; bj < 2; ++bj)
; #pragma unroll
;                         for (int n = 0; n < 2; ++n) acc[ai][bj][m][n] = acc[ai][bj][m][n] * r2; } }
;         u32x2v preb[2][4][2][2]; f32x4 pref[4][2][2];
; #pragma unroll
;         for (int ai = 0; ai < 2; ++ai)
; #pragma unroll
;             for (int m = 0; m < 4; ++m) { const size_t off = (size_t)(u.pm * BM + ai * HALF + wr * 64 + m * 16 + fr) * ldc + col0;
; #pragma unroll
;                 for (int bj = 0; bj < 2; ++bj)
; #pragma unroll
;                     for (int n = 0; n < 2; ++n) { if (BASEF32) { if (ai == 0) pref[m][bj][n] = *(const f32x4*)((const float*)base + off + bj * HALF + n * 16); }
;                                                   else if (!PRESCALE || ai == 0) preb[ai][m][bj][n] = *(const u32x2v*)((const bf16_t*)base + off + bj * HALF + n * 16); } }
	v_mov_b32_e32 v144, v141
	v_mov_b32_e32 v145, v142
	v_mov_b32_e32 v141, v143
	v_pk_add_f32 v[140:141], v[144:145], v[140:141]
	s_nop 0
	v_add_f32_e32 v3, v140, v141
	ds_bpermute_b32 v140, v184, v3
	s_waitcnt lgkmcnt(0)
	v_add_f32_e32 v191, v3, v140
	v_add_u32_e32 v140, 0xb0, v132
	v_ashrrev_i32_e32 v141, 31, v140
	v_lshlrev_b64 v[140:141], 6, v[140:141]
	v_lshl_add_u64 v[140:141], s[68:69], 0, v[140:141]
	v_lshl_add_u64 v[140:141], v[140:141], 0, v[0:1]
	global_load_dwordx4 v[140:143], v[140:141], off
	v_lshlrev_b64 v[132:133], 11, v[132:133]
	ds_bpermute_b32 v192, v185, v191
	s_waitcnt vmcnt(0)
	v_mov_b32_e32 v144, v141
	v_mov_b32_e32 v145, v142
	v_mov_b32_e32 v141, v143
	v_pk_add_f32 v[140:141], v[144:145], v[140:141]
	s_nop 0
	v_add_f32_e32 v0, v140, v141
	ds_bpermute_b32 v3, v184, v0
	s_waitcnt lgkmcnt(0)
	v_add_f32_e32 v0, v0, v3
	v_ashrrev_i32_e32 v3, 31, v2
	v_lshl_add_u64 v[182:183], v[2:3], 1, s[28:29]
	v_lshl_add_u64 v[132:133], v[182:183], 0, v[132:133]
	global_load_dwordx2 v[178:179], v[132:133], off
	global_load_dwordx2 v[176:177], v[132:133], off offset:32
	global_load_dwordx2 v[174:175], v[132:133], off offset:256
	global_load_dwordx2 v[172:173], v[132:133], off offset:288
	v_lshlrev_b64 v[132:133], 11, v[134:135]
	v_lshl_add_u64 v[132:133], v[182:183], 0, v[132:133]
	global_load_dwordx2 v[170:171], v[132:133], off
	global_load_dwordx2 v[168:169], v[132:133], off offset:32
	global_load_dwordx2 v[166:167], v[132:133], off offset:256
	global_load_dwordx2 v[164:165], v[132:133], off offset:288
	v_lshlrev_b64 v[132:133], 11, v[136:137]
	v_lshl_add_u64 v[132:133], v[182:183], 0, v[132:133]
	global_load_dwordx2 v[154:155], v[132:133], off
	global_load_dwordx2 v[144:145], v[132:133], off offset:32
	global_load_dwordx2 v[142:143], v[132:133], off offset:256
	global_load_dwordx2 v[140:141], v[132:133], off offset:288
	v_lshlrev_b64 v[132:133], 11, v[138:139]
	v_lshl_add_u64 v[132:133], v[182:183], 0, v[132:133]
	global_load_dwordx2 v[138:139], v[132:133], off
	global_load_dwordx2 v[136:137], v[132:133], off offset:32
	global_load_dwordx2 v[134:135], v[132:133], off offset:256
	s_nop 0
	global_load_dwordx2 v[132:133], v[132:133], off offset:288
	v_pk_mov_b32 v[182:183], v[162:163], v[160:161] op_sel:[1,0]
	ds_bpermute_b32 v190, v185, v0
	v_pk_add_f32 v[182:183], v[182:183], v[202:203]
	v_pk_mov_b32 v[202:203], v[158:159], v[156:157] op_sel:[1,0]
	v_add_f32_e32 v182, v182, v183
	v_pk_add_f32 v[202:203], v[202:203], v[210:211]
	v_add_f32_e32 v183, 0, v182
	v_pk_add_f32 v[202:203], v[202:203], v[202:203] op_sel_hi:[0,1]
	v_add_f32_e32 v211, v152, v153
	v_mov_b32_e32 v210, v148
	v_mov_b32_e32 v202, v146
	v_mov_b32_e32 v182, v147
	v_pk_add_f32 v[210:211], v[210:211], v[212:213]
	v_pk_add_f32 v[182:183], v[202:203], v[182:183]
	s_nop 0
	v_pk_add_f32 v[182:183], v[210:211], v[182:183]
	s_nop 0
	v_add_f32_e32 v182, v182, v183
	ds_bpermute_b32 v183, v184, v182
	s_waitcnt lgkmcnt(0)
	v_add_f32_e32 v182, v182, v183
	ds_bpermute_b32 v183, v185, v182
	s_waitcnt lgkmcnt(0)
	v_add_f32_e32 v182, v182, v183
	v_mul_f32_e32 v182, 0x3c800000, v182
	v_pk_fma_f32 v[128:129], v[128:129], v[180:181], v[182:183] op_sel_hi:[1,0,0] neg_lo:[0,0,1] neg_hi:[0,0,1]
	v_pk_fma_f32 v[124:125], v[124:125], v[180:181], v[182:183] op_sel_hi:[1,0,0] neg_lo:[0,0,1] neg_hi:[0,0,1]
	v_pk_fma_f32 v[130:131], v[130:131], v[180:181], v[182:183] op_sel_hi:[1,0,0] neg_lo:[0,0,1] neg_hi:[0,0,1]
	v_mul_f32_e32 v129, v129, v129
	v_pk_fma_f32 v[126:127], v[126:127], v[180:181], v[182:183] op_sel_hi:[1,0,0] neg_lo:[0,0,1] neg_hi:[0,0,1]
	v_mul_f32_e32 v125, v125, v125
	v_pk_fma_f32 v[120:121], v[120:121], v[180:181], v[182:183] op_sel_hi:[1,0,0] neg_lo:[0,0,1] neg_hi:[0,0,1]
	v_fmac_f32_e32 v129, v128, v128
	v_mul_f32_e32 v128, v131, v131
	v_fmac_f32_e32 v125, v124, v124
	v_mul_f32_e32 v124, v127, v127
	v_pk_fma_f32 v[122:123], v[122:123], v[180:181], v[182:183] op_sel_hi:[1,0,0] neg_lo:[0,0,1] neg_hi:[0,0,1]
	v_mul_f32_e32 v121, v121, v121
	v_pk_fma_f32 v[116:117], v[116:117], v[180:181], v[182:183] op_sel_hi:[1,0,0] neg_lo:[0,0,1] neg_hi:[0,0,1]
	v_fmac_f32_e32 v128, v130, v130
	v_fmac_f32_e32 v124, v126, v126
	v_fmac_f32_e32 v121, v120, v120
	v_mul_f32_e32 v120, v123, v123
	v_pk_fma_f32 v[118:119], v[118:119], v[180:181], v[182:183] op_sel_hi:[1,0,0] neg_lo:[0,0,1] neg_hi:[0,0,1]
	v_mul_f32_e32 v117, v117, v117
	v_add_f32_e32 v128, v129, v128
	v_add_f32_e32 v124, v125, v124
	v_fmac_f32_e32 v120, v122, v122
	v_fmac_f32_e32 v117, v116, v116
	v_mul_f32_e32 v116, v119, v119
	v_add_f32_e32 v124, v128, v124
	v_add_f32_e32 v120, v121, v120
	v_fmac_f32_e32 v116, v118, v118
	v_add_f32_e32 v120, v120, v124
	v_add_f32_e32 v116, v117, v116
	v_add_f32_e32 v116, v116, v120
	ds_bpermute_b32 v117, v184, v116
	s_waitcnt lgkmcnt(0)
	v_add_f32_e32 v116, v116, v117
	ds_bpermute_b32 v117, v185, v116
	s_and_saveexec_b64 s[6:7], s[4:5]
	v_readlane_b32 s0, v255, 11
	v_readlane_b32 s1, v255, 12
	s_load_dwordx2 s[56:57], s[0:1], 0x120
	v_readlane_b32 s55, v255, 9
	s_cbranch_execz .LBB0_1112
	s_lshl_b32 s8, s71, 11
	s_add_i32 s8, s3, s8
	v_lshl_add_u32 v118, v188, 5, s8
	s_waitcnt lgkmcnt(0)
	v_add_f32_e32 v183, v116, v117
	ds_write_b64 v118, v[182:183]

; __global__ void __launch_bounds__(NWAVES * 64) fwd_megakernel(Args args) {
	.amdhsa_kernel _Z14fwd_megakernel4Args
		.amdhsa_group_segment_fixed_size 0
		.amdhsa_private_segment_fixed_size 0
		.amdhsa_kernarg_size 544
		.amdhsa_user_sgpr_count 2
		.amdhsa_user_sgpr_dispatch_ptr 0
		.amdhsa_user_sgpr_queue_ptr 0
		.amdhsa_user_sgpr_kernarg_segment_ptr 1
		.amdhsa_user_sgpr_dispatch_id 0
		.amdhsa_user_sgpr_kernarg_preload_length 0
		.amdhsa_user_sgpr_kernarg_preload_offset 0
		.amdhsa_user_sgpr_private_segment_size 0
		.amdhsa_uses_dynamic_stack 0
		.amdhsa_enable_private_segment 0
		.amdhsa_system_sgpr_workgroup_id_x 1
		.amdhsa_system_sgpr_workgroup_id_y 0
		.amdhsa_system_sgpr_workgroup_id_z 0
		.amdhsa_system_sgpr_workgroup_info 0
		.amdhsa_system_vgpr_workitem_id 2
		.amdhsa_next_free_vgpr 256
		.amdhsa_next_free_sgpr 102
		.amdhsa_accum_offset 256
		.amdhsa_reserve_vcc 1
		.amdhsa_float_round_mode_32 0
		.amdhsa_float_round_mode_16_64 0
		.amdhsa_float_denorm_mode_32 3
		.amdhsa_float_denorm_mode_16_64 3
		.amdhsa_dx10_clamp 1
		.amdhsa_ieee_mode 1
		.amdhsa_fp16_overflow 0
		.amdhsa_tg_split 0
		.amdhsa_exception_fp_ieee_invalid_op 0
		.amdhsa_exception_fp_denorm_src 0
		.amdhsa_exception_fp_ieee_div_zero 0
		.amdhsa_exception_fp_ieee_overflow 0
		.amdhsa_exception_fp_ieee_underflow 0
		.amdhsa_exception_fp_ieee_inexact 0
		.amdhsa_exception_int_div_zero 0
	.end_amdhsa_kernel

; __global__ void __launch_bounds__(NWAVES * 64) fwd_megakernel(Args args) {
amdhsa.kernels:
  - .agpr_count:     0
    .args:
      - .offset:         0
        .size:           288
        .value_kind:     by_value
      - .offset:         288
        .size:           4
        .value_kind:     hidden_block_count_x
      - .offset:         292
        .size:           4
        .value_kind:     hidden_block_count_y
      - .offset:         296
        .size:           4
        .value_kind:     hidden_block_count_z
      - .offset:         300
        .size:           2
        .value_kind:     hidden_group_size_x
      - .offset:         302
        .size:           2
        .value_kind:     hidden_group_size_y
      - .offset:         304
        .size:           2
        .value_kind:     hidden_group_size_z
      - .offset:         306
        .size:           2
        .value_kind:     hidden_remainder_x
      - .offset:         308
        .size:           2
        .value_kind:     hidden_remainder_y
      - .offset:         310
        .size:           2
        .value_kind:     hidden_remainder_z
      - .offset:         328
        .size:           8
        .value_kind:     hidden_global_offset_x
      - .offset:         336
        .size:           8
        .value_kind:     hidden_global_offset_y
      - .offset:         344
        .size:           8
        .value_kind:     hidden_global_offset_z
      - .offset:         352
        .size:           2
        .value_kind:     hidden_grid_dims
      - .offset:         376
        .size:           8
        .value_kind:     hidden_multigrid_sync_arg
      - .offset:         408
        .size:           4
        .value_kind:     hidden_dynamic_lds_size
    .group_segment_fixed_size: 0
    .kernarg_segment_align: 8
    .kernarg_segment_size: 544
    .language:       OpenCL C
    .language_version:
      - 2
      - 0
    .max_flat_workgroup_size: 512
    .name:           _Z14fwd_megakernel4Args
    .private_segment_fixed_size: 0
    .sgpr_count:     108
    .sgpr_spill_count: 25
    .symbol:         _Z14fwd_megakernel4Args.kd
    .uniform_work_group_size: 1
    .uses_dynamic_stack: false
    .vgpr_count:     256
    .vgpr_spill_count: 0
    .wavefront_size: 64
